# mixprep stage C: conv taps + gate weight fragment loads issued at stage entry / before the conv loop into dead registers (counted vmcnt), latency hidden under LDS staging and conv
# speedup vs baseline: 1.0403x; 1.0010x over previous
.LBB0_306:
	s_load_dwordx2 s[98:99], s[78:79], 0x50
	s_load_dwordx2 s[100:101], s[78:79], 0x58
	v_lshlrev_b32_e32 v148, 4, v122
	v_mov_b32_e32 v149, 0
	s_mov_b32 s4, s3
	s_mov_b32 s5, 0
	s_mov_b64 s[6:7], 0x3000
	v_lshlrev_b32_e32 v117, 4, v116
	v_lshl_add_u64 v[150:151], s[16:17], 0, v[148:149]
	v_lshl_add_u64 v[152:153], v[150:151], 0, s[4:5]
	v_lshl_add_u64 v[154:155], v[150:151], 0, s[6:7]
	s_mov_b64 s[4:5], 0x1000
	v_lshl_add_u64 v[184:185], v[150:151], 0, s[4:5]
	global_load_dwordx4 v[26:29], v148, s[16:17] offset:3072
	global_load_dwordx4 v[30:33], v[154:155], off offset:-4096
	global_load_dwordx4 v[34:37], v[152:153], off offset:1024
	global_load_dwordx4 v[38:41], v[152:153], off offset:2048
	global_load_dwordx4 v[42:45], v[154:155], off
	global_load_dwordx4 v[46:49], v[154:155], off offset:1024
	global_load_dwordx4 v[50:53], v[154:155], off offset:2048
	global_load_dwordx4 v[54:57], v[154:155], off offset:3072
	global_load_dwordx4 v[58:61], v[152:153], off offset:3072
	global_load_dwordx4 v[62:65], v117, s[18:19]
	global_load_dwordx4 v[66:69], v117, s[18:19] offset:64
	global_load_dwordx4 v[70:73], v117, s[18:19] offset:128
	global_load_dwordx4 v[74:77], v117, s[18:19] offset:1088
	global_load_dwordx4 v[78:81], v117, s[18:19] offset:1152
	global_load_dwordx4 v[82:85], v117, s[18:19] offset:2112
	global_load_dwordx4 v[86:89], v117, s[18:19] offset:2176
	global_load_dwordx4 v[94:97], v117, s[18:19] offset:192
	global_load_dwordx4 v[102:105], v117, s[18:19] offset:1216
	global_load_dwordx4 v[106:109], v148, s[16:17]
	global_load_dwordx4 v[110:113], v117, s[18:19] offset:2240
	v_lshlrev_b32_e32 v156, 3, v91
	v_mov_b32_e32 v157, 0
	s_waitcnt lgkmcnt(0)
	s_add_u32 s98, s98, s20
	s_addc_u32 s99, s99, s21
	v_lshl_add_u64 v[158:159], s[98:99], 0, v[156:157]
	s_lshl_b64 s[98:99], s[12:13], 2
	s_add_u32 s98, s100, s98
	s_addc_u32 s99, s101, s99
	v_lshl_add_u64 v[170:171], s[98:99], 0, v[156:157]
	global_load_dwordx2 v[160:161], v[158:159], off
	global_load_dwordx2 v[162:163], v[158:159], off offset:1024
	global_load_dwordx2 v[164:165], v[158:159], off offset:2048
	global_load_dwordx2 v[166:167], v[158:159], off offset:3072
	global_load_dwordx2 v[168:169], v[170:171], off
	s_movk_i32 s4, 0x860
	v_add_u32_e32 v0, 0, v98
	v_cmp_gt_i32_e32 vcc, s4, v115
	s_and_saveexec_b64 s[4:5], vcc
	s_cbranch_execz .LBB0_308
	s_waitcnt vmcnt(25)
	v_ashrrev_i32_e32 v22, 5, v115
	v_mad_u64_u32 v[22:23], s[6:7], v22, s68, v[0:1]
	ds_write_b128 v22, v[6:9]
.LBB0_308:
	s_or_b64 exec, exec, s[4:5]
	s_movk_i32 s4, 0x660
	v_cmp_gt_i32_e32 vcc, s4, v115
	s_and_saveexec_b64 s[4:5], vcc
	s_cbranch_execz .LBB0_310
	s_waitcnt vmcnt(25)
	v_add_u32_e32 v6, 0x200, v115
	v_ashrrev_i32_e32 v6, 5, v6
	v_mad_u64_u32 v[6:7], s[6:7], v6, s68, v[0:1]
	ds_write_b128 v6, v[2:5]
.LBB0_310:
	s_or_b64 exec, exec, s[4:5]
	s_movk_i32 s4, 0x460
	v_cmp_gt_i32_e32 vcc, s4, v115
	s_and_saveexec_b64 s[4:5], vcc
	s_cbranch_execz .LBB0_312
	s_waitcnt vmcnt(25)
	v_add_u32_e32 v2, 0x400, v115
	v_ashrrev_i32_e32 v2, 5, v2
	v_mad_u64_u32 v[2:3], s[6:7], v2, s68, v[0:1]
	ds_write_b128 v2, v[14:17]
.LBB0_312:
	s_or_b64 exec, exec, s[4:5]
	s_movk_i32 s4, 0x260
	v_cmp_gt_i32_e32 vcc, s4, v115
	s_and_saveexec_b64 s[4:5], vcc
	s_cbranch_execz .LBB0_314
	s_waitcnt vmcnt(25)
	v_add_u32_e32 v2, 0x600, v115
	v_ashrrev_i32_e32 v2, 5, v2
	v_mad_u64_u32 v[2:3], s[6:7], v2, s68, v[0:1]
	ds_write_b128 v2, v[10:13]
.LBB0_314:
	s_or_b64 exec, exec, s[4:5]
	s_movk_i32 s4, 0x60
	v_cmp_gt_i32_e32 vcc, s4, v115
	s_and_saveexec_b64 s[4:5], vcc
	s_cbranch_execz .LBB0_316
	s_waitcnt vmcnt(25)
	v_add_u32_e32 v2, 0x800, v115
	v_ashrrev_i32_e32 v2, 5, v2
	v_mad_u64_u32 v[2:3], s[6:7], v2, s68, v[0:1]
	ds_write_b128 v2, v[18:21]
.LBB0_316:
	s_or_b64 exec, exec, s[4:5]
	s_waitcnt lgkmcnt(0)
	s_barrier
	v_lshlrev_b32_e32 v172, 2, v91
	v_lshrrev_b32_e32 v0, 7, v115
	s_movk_i32 s4, 0x2100
	v_mul_lo_u32 v0, v0, s4
	v_add3_u32 v0, v0, v172, 0
	s_mov_b32 s4, 0
	global_load_dwordx4 v[2:5], v148, s[16:17] offset:1024
	global_load_dwordx4 v[6:9], v148, s[16:17] offset:2048
	global_load_dwordx4 v[10:13], v[184:185], off
	global_load_dwordx4 v[14:17], v[184:185], off offset:1024
	global_load_dwordx4 v[18:21], v[184:185], off offset:2048
	global_load_dwordx4 v[22:25], v[184:185], off offset:3072
	global_load_dwordx4 v[90:93], v117, s[18:19] offset:1024
	global_load_dwordx4 v[98:101], v117, s[18:19] offset:2048
.LBB0_317:
	v_add_u32_e32 v182, s4, v0
	ds_read2_b32 v[172:173], v182 offset1:132
	v_add_u32_e32 v176, 0x400, v182
	ds_read2_b32 v[176:177], v176 offset0:8 offset1:140
	s_addk_i32 s4, 0x840
	s_cmpk_eq_i32 s4, 0x2100
	s_waitcnt lgkmcnt(0)
	v_lshlrev_b32_e32 v174, 16, v172
	v_and_b32_e32 v175, 0xffff0000, v172
	v_lshlrev_b32_e32 v172, 16, v173
	v_and_b32_e32 v173, 0xffff0000, v173
	s_waitcnt vmcnt(8)
	v_pk_fma_f32 v[174:175], v[160:161], v[174:175], v[168:169]
	v_lshlrev_b32_e32 v178, 16, v176
	v_and_b32_e32 v179, 0xffff0000, v176
	v_pk_fma_f32 v[174:175], v[162:163], v[172:173], v[174:175]
	v_lshlrev_b32_e32 v176, 16, v177
	v_and_b32_e32 v177, 0xffff0000, v177
	v_pk_fma_f32 v[174:175], v[164:165], v[178:179], v[174:175]
	v_pk_fma_f32 v[172:173], v[160:161], v[172:173], v[168:169]
	v_pk_fma_f32 v[174:175], v[166:167], v[176:177], v[174:175]
	v_pk_fma_f32 v[172:173], v[162:163], v[178:179], v[172:173]
	v_cvt_pk_bf16_f32 v183, v174, v175
	v_add_u32_e32 v174, 0x800, v182
	ds_read2_b32 v[174:175], v174 offset0:16 offset1:148
	v_pk_fma_f32 v[172:173], v[164:165], v[176:177], v[172:173]
	s_waitcnt lgkmcnt(0)
	v_lshlrev_b32_e32 v180, 16, v174
	v_and_b32_e32 v181, 0xffff0000, v174
	v_pk_fma_f32 v[172:173], v[166:167], v[180:181], v[172:173]
	s_nop 0
	v_cvt_pk_bf16_f32 v172, v172, v173
	v_add_u32_e32 v173, 0x8c00, v182
	ds_write2_b32 v173, v183, v172 offset1:132
	v_lshlrev_b32_e32 v172, 16, v175
	v_and_b32_e32 v173, 0xffff0000, v175
	v_pk_fma_f32 v[174:175], v[160:161], v[178:179], v[168:169]
	s_nop 0
	v_pk_fma_f32 v[174:175], v[162:163], v[176:177], v[174:175]
	v_pk_fma_f32 v[176:177], v[160:161], v[176:177], v[168:169]
	v_pk_fma_f32 v[174:175], v[164:165], v[180:181], v[174:175]
	v_pk_fma_f32 v[176:177], v[162:163], v[180:181], v[176:177]
	v_pk_fma_f32 v[174:175], v[166:167], v[172:173], v[174:175]
	v_pk_fma_f32 v[172:173], v[164:165], v[172:173], v[176:177]
	v_cvt_pk_bf16_f32 v178, v174, v175
	ds_read_b32 v175, v182 offset:3168
	s_waitcnt lgkmcnt(0)
	v_lshlrev_b32_e32 v174, 16, v175
	v_and_b32_e32 v175, 0xffff0000, v175
	v_pk_fma_f32 v[172:173], v[166:167], v[174:175], v[172:173]
	s_nop 0
	v_cvt_pk_bf16_f32 v172, v172, v173
	v_add_u32_e32 v173, 0x9000, v182
	ds_write2_b32 v173, v178, v172 offset0:8 offset1:140
	s_cbranch_scc0 .LBB0_317
	s_waitcnt lgkmcnt(0)
	s_barrier
	v_readlane_b32 s5, v252, 45
	v_and_b32_e32 v115, 48, v115
	v_readlane_b32 s6, v252, 51
	v_add_u32_e32 v123, s5, v115
	v_mul_u32_u24_e32 v115, 0x44, v124
	v_lshlrev_b32_e32 v115, 2, v115
	v_readlane_b32 s8, v252, 53
	v_add3_u32 v125, s6, v117, v115
	v_add3_u32 v131, s6, v115, v117
	v_mov_b32_e32 v115, v1
	v_readlane_b32 s9, v252, 54
	s_mov_b32 s4, 0
	v_lshl_add_u32 v0, v116, 3, s5
	s_ashr_i32 s5, s22, 31
	v_lshl_add_u64 v[126:127], s[8:9], 0, v[114:115]
	v_add_u32_e32 v132, s6, v114
	v_mov_b32_e32 v129, 0
	v_mov_b32_e32 v130, 1.0
	s_waitcnt vmcnt(0)
